# P3 scan loops: tile-pointer+constant 64-bit VALU adds replaced by SGPR-base + 32-bit offset addressing; int8 ya store offset in 32-bit ops
# baseline (speedup 1.0000x reference)
; __device__ __forceinline__ unsigned cvt_pk_bf16(float lo, float hi) { unsigned r; asm volatile("v_cvt_pk_bf16_f32 %0, %1, %2" : "=v"(r) : "v"(lo), "v"(hi)); return r; }
; __device__ __forceinline__ void s5_phase(const Args& a, const Ctx& F) {
;     ...
;     for (int tile = 0; tile < 4; ++tile) {
;         bf16x8 A01[2];
; #pragma unroll
;         for (int sx = 0; sx < 2; ++sx) {
;             const int q = tile * 64 + 2 * nl + hl, t = d ? (CTXL - 1 - q) : q;
;             const float* p0 = UCP + (size_t)(b * CTXL + t) * EI + chan0 + 8 * sx;
;             f32x4 lo = *(const f32x4*)p0, hi = *(const f32x4*)(p0 + 4);
; #pragma unroll
;             for (int k = 1; k < 4; ++k) { lo += *(const f32x4*)(p0 + (size_t)k * MC * EI); hi += *(const f32x4*)(p0 + (size_t)k * MC * EI + 4); }
;             u32x4 w; w.x = cvt_pk_bf16(lo[0], lo[1]); w.y = cvt_pk_bf16(lo[2], lo[3]); w.z = cvt_pk_bf16(hi[0], hi[1]); w.w = cvt_pk_bf16(hi[2], hi[3]);
;             A01[sx] = __builtin_bit_cast(bf16x8, w);
;         }
;         S5_STATE_IN(A01[0], A01[1])
; #pragma unroll
;         for (int i = 0; i < 32; ++i) {
;             const int r = (i & 3) + 4 * (i >> 3); const bool up = (i >> 2) & 1;
;             const float sr = up ? sre1[r] : sre0[r], si = up ? sim1[r] : sim0[r];
;             const float nre = __builtin_fmaf(lr, hre, __builtin_fmaf(nli, him, sr)), nim = __builtin_fmaf(lr, him, __builtin_fmaf(li, hre, si)); hre = nre; him = nim;
;         }
.LBB0_377:
	v_add_u32_e32 v0, s6, v144
	v_cndmask_b32_e64 v0, v0, v145, s[0:1]
	v_add_u32_e32 v0, s7, v0
	v_ashrrev_i32_e32 v1, 31, v0
	v_lshlrev_b64 v[0:1], 15, v[0:1]
	v_lshl_add_u64 v[36:37], s[8:9], 0, v[0:1]
	v_add_co_u32_e32 v38, vcc, 0x1000000, v36
	v_lshl_add_u64 v[12:13], v[36:37], 0, s[10:11]
	s_nop 0
	v_addc_co_u32_e32 v39, vcc, 0, v37, vcc
	v_add_co_u32_e32 v40, vcc, s43, v36
	global_load_dwordx4 v[0:3], v[36:37], off offset:16
	global_load_dwordx4 v[4:7], v[36:37], off
	v_addc_co_u32_e32 v41, vcc, 0, v37, vcc
	v_lshl_add_u64 v[20:21], v[36:37], 0, s[16:17]
	global_load_dwordx4 v[8:11], v[38:39], off
	s_nop 0
	global_load_dwordx4 v[12:15], v[12:13], off offset:16
	v_add_co_u32_e32 v42, vcc, s46, v36
	v_lshl_add_u64 v[28:29], v[36:37], 0, s[18:19]
	global_load_dwordx4 v[16:19], v[40:41], off
	s_nop 0
	global_load_dwordx4 v[20:23], v[20:21], off offset:16
	v_addc_co_u32_e32 v43, vcc, 0, v37, vcc
	global_load_dwordx4 v[24:27], v[42:43], off
	s_nop 0
	global_load_dwordx4 v[28:31], v[28:29], off offset:16
	v_lshl_add_u64 v[44:45], v[36:37], 0, s[40:41]
	s_sub_i32 s6, s6, 64
	v_add_u32_e32 v145, 64, v145
	s_cmp_eq_u32 s6, -1
	s_waitcnt vmcnt(5)
	v_pk_add_f32 v[6:7], v[6:7], v[10:11]
	v_pk_add_f32 v[4:5], v[4:5], v[8:9]
	s_waitcnt vmcnt(4)
	v_pk_add_f32 v[2:3], v[2:3], v[14:15]
	v_pk_add_f32 v[0:1], v[0:1], v[12:13]
	s_waitcnt vmcnt(3)
	v_pk_add_f32 v[6:7], v[6:7], v[18:19]
	v_pk_add_f32 v[4:5], v[4:5], v[16:17]
	s_waitcnt vmcnt(2)
	v_pk_add_f32 v[2:3], v[2:3], v[22:23]
	v_pk_add_f32 v[0:1], v[0:1], v[20:21]
	s_waitcnt vmcnt(1)
	v_pk_add_f32 v[6:7], v[6:7], v[26:27]
	v_pk_add_f32 v[4:5], v[4:5], v[24:25]
	s_waitcnt vmcnt(0)
	v_pk_add_f32 v[2:3], v[2:3], v[30:31]
	v_pk_add_f32 v[0:1], v[0:1], v[28:29]
	v_cvt_pk_bf16_f32 v32, v4, v5
	v_cvt_pk_bf16_f32 v33, v6, v7
	v_lshl_add_u64 v[16:17], v[36:37], 0, s[22:23]
	v_cvt_pk_bf16_f32 v34, v0, v1
	v_cvt_pk_bf16_f32 v35, v2, v3
	global_load_dwordx4 v[146:149], v[36:37], off offset:48
	global_load_dwordx4 v[150:153], v[36:37], off offset:32
	global_load_dwordx4 v[166:169], v[38:39], off offset:32
	v_lshl_add_u64 v[18:19], v[36:37], 0, s[38:39]
	global_load_dwordx4 v[176:179], v[16:17], off offset:16
	global_load_dwordx4 v[180:183], v[40:41], off offset:32
	global_load_dwordx4 v[184:187], v[18:19], off offset:16
	global_load_dwordx4 v[188:191], v[42:43], off offset:32
	global_load_dwordx4 v[192:195], v[44:45], off offset:16
	v_mfma_f32_32x32x16_bf16 v[0:15], v[32:35], v[108:111], 0
	s_waitcnt vmcnt(4)
	v_add_f32_e64 v148, v148, v178
	v_add_f32_e64 v149, v149, v179
	v_mfma_f32_32x32x16_bf16 v[48:63], v[32:35], v[112:115], 0
	v_add_f32_e64 v146, v146, v176
	v_add_f32_e64 v147, v147, v177
	v_add_f32_e64 v152, v152, v168
	v_add_f32_e64 v153, v153, v169
	v_add_f32_e64 v150, v150, v166
	v_add_f32_e64 v151, v151, v167
	s_waitcnt vmcnt(2)
	v_pk_add_f32 v[148:149], v[148:149], v[186:187]
	v_pk_add_f32 v[146:147], v[146:147], v[184:185]
	v_pk_add_f32 v[152:153], v[152:153], v[182:183]
	v_pk_add_f32 v[150:151], v[150:151], v[180:181]
	v_mfma_f32_32x32x16_bf16 v[16:31], v[32:35], v[116:119], 0
	s_waitcnt vmcnt(0)
	v_add_f32_e64 v154, v148, v194
	v_add_f32_e64 v155, v149, v195
	v_add_f32_e64 v148, v146, v192
	v_add_f32_e64 v149, v147, v193
	v_pk_add_f32 v[152:153], v[152:153], v[190:191]
	v_pk_add_f32 v[150:151], v[150:151], v[188:189]
	s_nop 0
	v_cvt_pk_bf16_f32 v146, v150, v151
	v_cvt_pk_bf16_f32 v147, v152, v153
	v_mfma_f32_32x32x16_bf16 v[32:47], v[32:35], v[120:123], 0
	v_cvt_pk_bf16_f32 v148, v148, v149
	v_cvt_pk_bf16_f32 v149, v154, v155
	s_nop 0
	v_mfma_f32_32x32x16_bf16 v[0:15], v[146:149], v[124:127], v[0:15]
	v_mfma_f32_32x32x16_bf16 v[48:63], v[146:149], v[128:131], v[48:63]
	v_mfma_f32_32x32x16_bf16 v[16:31], v[146:149], v[132:135], v[16:31]
	v_mfma_f32_32x32x16_bf16 v[32:47], v[146:149], v[136:139], v[32:47]
	s_nop 10
	v_permlane32_swap_b32_e32 v0, v16
	v_permlane32_swap_b32_e32 v4, v20
	v_permlane32_swap_b32_e32 v8, v24
	v_permlane32_swap_b32_e32 v14, v30
	v_permlane32_swap_b32_e32 v48, v32
	v_permlane32_swap_b32_e32 v52, v36
	v_permlane32_swap_b32_e32 v53, v37
	v_permlane32_swap_b32_e32 v56, v40
	v_permlane32_swap_b32_e32 v57, v41
	v_permlane32_swap_b32_e32 v62, v46
	v_permlane32_swap_b32_e32 v63, v47
	v_mov_b32_e32 v152, v48
	v_mov_b32_e32 v153, v0
	v_permlane32_swap_b32_e32 v1, v17
	v_mov_b32_e32 v148, v20
	v_mov_b32_e32 v149, v36
	v_mov_b32_e32 v20, v37
	v_mov_b32_e32 v36, v56
	v_mov_b32_e32 v37, v8
	v_mov_b32_e32 v8, v57
	v_mov_b32_e32 v56, v46
	v_mov_b32_e32 v57, v30
	v_mov_b32_e32 v30, v47
	v_pk_fma_f32 v[46:47], v[172:173], v[164:165], v[152:153] op_sel:[0,1,0] op_sel_hi:[1,0,1]
	v_permlane32_swap_b32_e32 v49, v33
	v_mov_b32_e32 v48, v1
	v_pk_fma_f32 v[46:47], v[158:159], v[164:165], v[46:47]
	v_permlane32_swap_b32_e32 v2, v18
	v_permlane32_swap_b32_e32 v50, v34
	v_pk_fma_f32 v[48:49], v[174:175], v[46:47], v[48:49]
	v_mov_b32_e32 v146, v2
	v_mov_b32_e32 v147, v50
	v_pk_fma_f32 v[46:47], v[158:159], v[46:47], v[48:49] op_sel:[0,0,1] op_sel_hi:[1,1,0]
	v_permlane32_swap_b32_e32 v51, v35
	v_pk_fma_f32 v[48:49], v[142:143], v[46:47], v[146:147]
	v_permlane32_swap_b32_e32 v3, v19
	v_mov_b32_e32 v2, v51
	v_pk_fma_f32 v[46:47], v[158:159], v[46:47], v[48:49] op_sel:[0,0,1] op_sel_hi:[1,1,0]
	v_mov_b32_e32 v0, v32
	v_pk_fma_f32 v[2:3], v[160:161], v[46:47], v[2:3] op_sel:[0,1,0] op_sel_hi:[1,0,1]
	v_mov_b32_e32 v1, v16
	v_pk_fma_f32 v[2:3], v[158:159], v[46:47], v[2:3]
	v_mov_b32_e32 v16, v33
	v_pk_fma_f32 v[0:1], v[160:161], v[2:3], v[0:1] op_sel:[0,1,0] op_sel_hi:[1,0,1]
	v_mov_b32_e32 v32, v34
	v_pk_fma_f32 v[0:1], v[158:159], v[2:3], v[0:1]
	v_mov_b32_e32 v33, v18
; __device__ __forceinline__ void s5_phase(const Args& a, const Ctx& F) {
;     ...
;         S5_STATE_IN(A01[0], A01[1])
; #pragma unroll
;         for (int i = 0; i < 32; ++i) {
;             const int r = (i & 3) + 4 * (i >> 3); const bool up = (i >> 2) & 1;
;             const float sr = up ? sre1[r] : sre0[r], si = up ? sim1[r] : sim0[r];
;             const float nre = __builtin_fmaf(lr, hre, __builtin_fmaf(nli, him, sr)), nim = __builtin_fmaf(lr, him, __builtin_fmaf(li, hre, si)); hre = nre; him = nim;
;         }
	v_pk_fma_f32 v[2:3], v[160:161], v[0:1], v[16:17] op_sel:[0,1,0] op_sel_hi:[1,0,1]
	v_mov_b32_e32 v18, v35
	v_pk_fma_f32 v[0:1], v[158:159], v[0:1], v[2:3]
	v_mov_b32_e32 v34, v52
	v_pk_fma_f32 v[2:3], v[160:161], v[0:1], v[32:33] op_sel:[0,1,0] op_sel_hi:[1,0,1]
	v_mov_b32_e32 v35, v4
	v_pk_fma_f32 v[0:1], v[158:159], v[0:1], v[2:3]
	v_permlane32_swap_b32_e32 v5, v21
	v_pk_fma_f32 v[2:3], v[160:161], v[0:1], v[18:19] op_sel:[0,1,0] op_sel_hi:[1,0,1]
	v_mov_b32_e32 v4, v53
	v_pk_fma_f32 v[0:1], v[158:159], v[0:1], v[2:3]
	v_permlane32_swap_b32_e32 v6, v22
	v_pk_fma_f32 v[2:3], v[160:161], v[0:1], v[34:35] op_sel:[0,1,0] op_sel_hi:[1,0,1]
	v_permlane32_swap_b32_e32 v54, v38
	v_pk_fma_f32 v[0:1], v[158:159], v[0:1], v[2:3]
	v_mov_b32_e32 v50, v54
	v_pk_fma_f32 v[2:3], v[160:161], v[0:1], v[4:5] op_sel:[0,1,0] op_sel_hi:[1,0,1]
	v_mov_b32_e32 v51, v6
	v_pk_fma_f32 v[0:1], v[158:159], v[0:1], v[2:3]
	v_permlane32_swap_b32_e32 v7, v23
	v_pk_fma_f32 v[2:3], v[160:161], v[0:1], v[50:51] op_sel:[0,1,0] op_sel_hi:[1,0,1]
	v_permlane32_swap_b32_e32 v55, v39
	v_mov_b32_e32 v54, v7
	v_pk_fma_f32 v[0:1], v[158:159], v[0:1], v[2:3]
	v_mov_b32_e32 v6, v38
	v_pk_fma_f32 v[2:3], v[142:143], v[0:1], v[54:55]
	v_mov_b32_e32 v7, v22
	v_pk_fma_f32 v[0:1], v[158:159], v[0:1], v[2:3] op_sel:[0,0,1] op_sel_hi:[1,1,0]
	v_mov_b32_e32 v22, v39
	v_pk_fma_f32 v[2:3], v[142:143], v[0:1], v[148:149]
	v_permlane32_swap_b32_e32 v9, v25
	v_pk_fma_f32 v[0:1], v[158:159], v[0:1], v[2:3] op_sel:[0,0,1] op_sel_hi:[1,1,0]
	v_permlane32_swap_b32_e32 v10, v26
	v_pk_fma_f32 v[2:3], v[160:161], v[0:1], v[20:21] op_sel:[0,1,0] op_sel_hi:[1,0,1]
	v_permlane32_swap_b32_e32 v58, v42
	v_pk_fma_f32 v[0:1], v[158:159], v[0:1], v[2:3]
	v_mov_b32_e32 v38, v40
	v_pk_fma_f32 v[2:3], v[160:161], v[0:1], v[6:7] op_sel:[0,1,0] op_sel_hi:[1,0,1]
	v_mov_b32_e32 v39, v24
	v_pk_fma_f32 v[0:1], v[158:159], v[0:1], v[2:3]
	v_mov_b32_e32 v40, v25
	v_pk_fma_f32 v[2:3], v[160:161], v[0:1], v[22:23] op_sel:[0,1,0] op_sel_hi:[1,0,1]
	v_mov_b32_e32 v24, v58
	v_pk_fma_f32 v[0:1], v[158:159], v[0:1], v[2:3]
	v_mov_b32_e32 v25, v10
	v_pk_fma_f32 v[2:3], v[160:161], v[0:1], v[36:37] op_sel:[0,1,0] op_sel_hi:[1,0,1]
	v_permlane32_swap_b32_e32 v59, v43
	v_pk_fma_f32 v[0:1], v[158:159], v[0:1], v[2:3]
	v_permlane32_swap_b32_e32 v11, v27
	v_pk_fma_f32 v[2:3], v[160:161], v[0:1], v[8:9] op_sel:[0,1,0] op_sel_hi:[1,0,1]
	v_mov_b32_e32 v10, v59
	v_pk_fma_f32 v[0:1], v[158:159], v[0:1], v[2:3]
	v_mov_b32_e32 v150, v26
	v_pk_fma_f32 v[2:3], v[160:161], v[0:1], v[24:25] op_sel:[0,1,0] op_sel_hi:[1,0,1]
	v_mov_b32_e32 v151, v42
	v_pk_fma_f32 v[0:1], v[158:159], v[0:1], v[2:3]
	v_mov_b32_e32 v26, v43
	v_pk_fma_f32 v[2:3], v[160:161], v[0:1], v[10:11] op_sel:[0,1,0] op_sel_hi:[1,0,1]
	v_permlane32_swap_b32_e32 v12, v28
	v_pk_fma_f32 v[0:1], v[158:159], v[0:1], v[2:3]
	v_permlane32_swap_b32_e32 v60, v44
	v_pk_fma_f32 v[2:3], v[160:161], v[0:1], v[38:39] op_sel:[0,1,0] op_sel_hi:[1,0,1]
	v_mov_b32_e32 v42, v60
	v_pk_fma_f32 v[0:1], v[158:159], v[0:1], v[2:3]
	v_mov_b32_e32 v43, v12
	v_pk_fma_f32 v[2:3], v[142:143], v[0:1], v[40:41]
	v_permlane32_swap_b32_e32 v61, v45
	v_pk_fma_f32 v[0:1], v[158:159], v[0:1], v[2:3] op_sel:[0,0,1] op_sel_hi:[1,1,0]
	v_permlane32_swap_b32_e32 v13, v29
	v_pk_fma_f32 v[2:3], v[142:143], v[0:1], v[150:151]
	v_mov_b32_e32 v12, v61
	v_pk_fma_f32 v[0:1], v[158:159], v[0:1], v[2:3] op_sel:[0,0,1] op_sel_hi:[1,1,0]
	v_mov_b32_e32 v52, v44
	v_pk_fma_f32 v[2:3], v[160:161], v[0:1], v[26:27] op_sel:[0,1,0] op_sel_hi:[1,0,1]
	v_mov_b32_e32 v53, v28
	v_pk_fma_f32 v[0:1], v[158:159], v[0:1], v[2:3]
	v_mov_b32_e32 v28, v45
	v_pk_fma_f32 v[2:3], v[160:161], v[0:1], v[42:43] op_sel:[0,1,0] op_sel_hi:[1,0,1]
	v_mov_b32_e32 v44, v62
	v_pk_fma_f32 v[0:1], v[158:159], v[0:1], v[2:3]
	v_mov_b32_e32 v45, v14
	v_pk_fma_f32 v[2:3], v[160:161], v[0:1], v[12:13] op_sel:[0,1,0] op_sel_hi:[1,0,1]
	v_permlane32_swap_b32_e32 v15, v31
	v_pk_fma_f32 v[0:1], v[158:159], v[0:1], v[2:3]
	v_mov_b32_e32 v14, v63
	v_pk_fma_f32 v[2:3], v[160:161], v[0:1], v[44:45] op_sel:[0,1,0] op_sel_hi:[1,0,1]
	s_nop 0
	v_pk_fma_f32 v[0:1], v[158:159], v[0:1], v[2:3]
	s_nop 0
	v_pk_fma_f32 v[2:3], v[160:161], v[0:1], v[14:15] op_sel:[0,1,0] op_sel_hi:[1,0,1]
	s_nop 0
	v_pk_fma_f32 v[0:1], v[158:159], v[0:1], v[2:3]
	s_nop 0
	v_pk_fma_f32 v[2:3], v[160:161], v[0:1], v[52:53] op_sel:[0,1,0] op_sel_hi:[1,0,1]
	s_nop 0
	v_pk_fma_f32 v[0:1], v[158:159], v[0:1], v[2:3]
	s_nop 0
	v_pk_fma_f32 v[2:3], v[160:161], v[0:1], v[28:29] op_sel:[0,1,0] op_sel_hi:[1,0,1]
	s_nop 0
	v_pk_fma_f32 v[0:1], v[158:159], v[0:1], v[2:3]
	s_nop 0
	v_pk_fma_f32 v[2:3], v[160:161], v[0:1], v[56:57] op_sel:[0,1,0] op_sel_hi:[1,0,1]
	s_nop 0
	v_pk_fma_f32 v[0:1], v[158:159], v[0:1], v[2:3]
	s_nop 0
	v_pk_fma_f32 v[2:3], v[160:161], v[0:1], v[30:31] op_sel:[0,1,0] op_sel_hi:[1,0,1]
	s_nop 0
	v_pk_fma_f32 v[164:165], v[158:159], v[0:1], v[2:3]
	s_cbranch_scc0 .LBB0_377
; #define LAS __attribute__((address_space(3)))
; template <bool REV> ...
;     constexpr int SG = REV ? -1 : 1;
;     constexpr int TSTEP = SG * 64 * 16, CSTEP16 = SG * 32 * 16, SSTEP = SG * 16;
;     const float nli = -li;
;     const int nl = lane & 31, hl = lane >> 5, tk = lane & 15, kq = lane >> 4;
;     const bf16* pA = U + gbase + SG * (2 * nl + hl) * 16;
;     const bf16* pB = U + gbase + SG * (2 * tk + (kq >> 1)) * 16 + 8 * (kq & 1);
;     const bf16* pU = U + gbase + SG * (2 * tk) * 16 + 4 * kq;
;     bf16* pY = YA + gbase + SG * (2 * tk) * 16 + 4 * kq;
;     bf16x8 A0 = *(const bf16x8*)pA, A1 = *(const bf16x8*)(pA + 8);
;     bf16x8 Ub[2]; Ub[0] = *(const bf16x8*)pB; Ub[1] = *(const bf16x8*)(pB + CSTEP16);
;     u32x2 pv[2][2], uv[2][2];
; #pragma unroll
;     for (int th = 0; th < 2; ++th)
; #pragma unroll
;         for (int sx = 0; sx < 2; ++sx) { pv[th][sx] = (u32x2){0u, 0u}; uv[th][sx] = (u32x2){0u, 0u}; }
;     const f32x2 dsk01 = (f32x2){dsk[0], dsk[1]}, dsk23 = (f32x2){dsk[2], dsk[3]};
;     LAS unsigned* wbase = (LAS unsigned*)(my + ((lane & 3) << 2));
; __device__ __forceinline__ void s5_phase(const Args& a, const Ctx& F) {
;     ...
;     const size_t gbase = ((size_t)(b * NG + g) * SEQ + (d ? SEQ - 1 : 0)) * 16;
;     unsigned char* Y8 = ws + WS_YA8;
;     if (d) s5_latent<true>(U, YA, Y8, gbase, Bf, Cf, Kf, lr, li, hre, him, my, dsk, lane);
;     else s5_latent<false>(U, YA, Y8, gbase, Bf, Cf, Kf, lr, li, hre, him, my, dsk, lane);
	s_add_u32 s6, s30, 0x4c400000
	s_addc_u32 s7, s31, 0
	s_lshl_b32 s19, s42, 9
	s_or_b32 s10, s35, s19
	s_ashr_i32 s11, s10, 31
	s_and_b64 s[0:1], s[0:1], exec
	s_cselect_b32 s0, 0, 0x1fff0
	s_add_u32 s8, s30, 0x70400000
	s_addc_u32 s9, s31, 0
	s_lshl_b32 s1, s95, 13
	s_add_i32 s35, s1, 0
	s_lshl_b32 s23, s0, 1
	s_lshl_b64 s[0:1], s[10:11], 18
	s_or_b32 s0, s0, s23
	s_add_u32 s0, s30, s0
	v_ashrrev_i32_e32 v207, 4, v140
	s_addc_u32 s1, s31, s1
	v_lshlrev_b32_e32 v0, 3, v207
	s_add_u32 s10, s0, 0x2bc00000
	v_and_b32_e32 v206, 15, v140
	v_and_b32_e32 v0, 8, v0
	s_mov_b64 s[16:17], 0x4c400000
	s_mov_b32 s52, 0
	s_addc_u32 s11, s1, 0
	v_mov_b32_e32 v163, 0
	s_and_b64 vcc, exec, s[12:13]
	v_lshlrev_b32_e32 v170, 4, v141
	v_lshlrev_b32_e32 v162, 1, v0
	v_lshlrev_b32_e32 v166, 2, v207
	v_lshlrev_b32_e32 v213, 2, v140
	v_and_b32_e32 v212, -4, v140
	v_lshl_add_u32 v205, v206, 8, s35
	v_lshrrev_b32_e32 v208, 1, v206
	v_bitop3_b32 v214, v140, 4, -4 bitop3:0x6c
	v_bitop3_b32 v215, v140, 8, -4 bitop3:0x6c
	v_bitop3_b32 v216, v140, 12, -4 bitop3:0x6c
	v_bitop3_b32 v217, v140, 16, -4 bitop3:0x6c
	v_bitop3_b32 v218, v140, 20, -4 bitop3:0x6c
	v_bitop3_b32 v219, v140, 24, -4 bitop3:0x6c
	v_bitop3_b32 v220, v140, 28, -4 bitop3:0x6c
	v_bitop3_b32 v221, v140, 32, -4 bitop3:0x6c
	v_bitop3_b32 v222, v140, 36, -4 bitop3:0x6c
	v_bitop3_b32 v223, v140, 40, -4 bitop3:0x6c
	v_bitop3_b32 v224, v140, 44, -4 bitop3:0x6c
	v_bitop3_b32 v225, v140, 48, -4 bitop3:0x6c
	v_bitop3_b32 v226, v140, 52, -4 bitop3:0x6c
	v_bitop3_b32 v227, v140, 56, -4 bitop3:0x6c
	v_bitop3_b32 v228, v140, 60, -4 bitop3:0x6c
	v_add_u32_e32 v211, 4, v207
	v_add_u32_e32 v210, 8, v207
	v_add_u32_e32 v209, 12, v207
	v_and_b32_e32 v168, 16, v140
	s_cbranch_vccz .LBB0_399
	v_mul_i32_i24_e32 v4, -2, v206
	v_sub_u32_e32 v4, v4, v204
	v_sub_u32_e32 v0, 0, v170
	v_lshlrev_b32_e32 v4, 4, v4
	v_ashrrev_i32_e32 v1, 31, v0
	v_ashrrev_i32_e32 v5, 31, v4
	v_lshlrev_b64 v[0:1], 1, v[0:1]
	v_lshlrev_b64 v[4:5], 1, v[4:5]
	v_lshl_add_u64 v[2:3], s[10:11], 0, v[0:1]
	v_lshl_add_u64 v[6:7], s[10:11], 0, v[4:5]
	v_lshl_add_u64 v[6:7], v[6:7], 0, v[162:163]
	global_load_dwordx4 v[152:155], v[2:3], off
	global_load_dwordx4 v[148:151], v[2:3], off offset:16
	global_load_dwordx4 v[144:147], v[6:7], off
	global_load_dwordx4 v[140:143], v[6:7], off offset:-1024
	s_add_i32 s0, s19, s33
	s_add_i32 s0, s0, s34
	s_ashr_i32 s1, s0, 31
	s_lshl_b64 s[0:1], s[0:1], 18
	s_or_b32 s0, s0, s23
	s_add_u32 s12, s30, s0
	s_addc_u32 s13, s31, s1
	v_mov_b32_e32 v169, v163
	v_mul_i32_i24_e32 v8, 0xffffffe0, v206
	v_and_b32_e32 v2, 12, v213
	v_lshl_add_u64 v[194:195], s[12:13], 0, v[0:1]
	v_lshl_add_u64 v[0:1], s[0:1], 0, v[168:169]
	v_ashrrev_i32_e32 v9, 31, v8
	v_add_u32_e32 v2, s35, v2
	v_lshl_add_u64 v[0:1], v[0:1], 0, v[4:5]
	v_ashrrev_i32_e32 v167, 31, v166
	v_lshl_add_u32 v248, v212, 2, v2
	v_lshl_add_u32 v247, v214, 2, v2
	v_lshl_add_u32 v246, v215, 2, v2
	v_lshl_add_u32 v245, v216, 2, v2
	v_lshl_add_u32 v244, v217, 2, v2
	v_lshl_add_u32 v243, v218, 2, v2
	v_lshl_add_u32 v242, v219, 2, v2
	v_lshl_add_u32 v241, v220, 2, v2
	v_lshl_add_u32 v240, v221, 2, v2
	v_lshl_add_u32 v239, v222, 2, v2
	v_lshl_add_u32 v238, v223, 2, v2
	v_lshl_add_u32 v237, v224, 2, v2
	v_lshl_add_u32 v232, v225, 2, v2
	v_lshl_add_u32 v231, v226, 2, v2
	v_lshl_add_u32 v230, v227, 2, v2
	v_lshl_add_u32 v229, v228, 2, v2
	v_xor_b32_e32 v2, v208, v207
	v_xor_b32_e32 v3, v211, v208
	v_xor_b32_e32 v6, v210, v208
	v_xor_b32_e32 v7, v209, v208
	v_bitop3_b32 v10, v208, v207, 8 bitop3:0x36
	v_bitop3_b32 v11, v208, v211, 8 bitop3:0x36
	v_bitop3_b32 v12, v208, v210, 8 bitop3:0x36
	v_bitop3_b32 v13, v208, v209, 8 bitop3:0x36
	v_lshl_add_u64 v[196:197], s[30:31], 0, v[0:1]
	v_lshl_add_u64 v[0:1], v[8:9], 1, s[0:1]
	v_lshlrev_b32_e32 v2, 4, v2
	v_lshlrev_b32_e32 v3, 4, v3
	v_lshlrev_b32_e32 v6, 4, v6
	v_lshlrev_b32_e32 v7, 4, v7
	v_lshlrev_b32_e32 v10, 4, v10
	v_lshlrev_b32_e32 v11, 4, v11
	v_lshlrev_b32_e32 v12, 4, v12
	v_lshlrev_b32_e32 v13, 4, v13
	v_lshl_add_u64 v[0:1], v[166:167], 1, v[0:1]
	v_mov_b32_e32 v176, v163
	v_mov_b32_e32 v177, v163
	s_sub_u32 s76, 0x10000000, s30
	s_add_u32 s78, s30, 0x1bc00000
	s_addc_u32 s79, s31, 0
	s_add_u32 s80, s30, 0x3c3ff000
	s_addc_u32 s81, s31, 0
	s_add_u32 s82, s30, 0x1bbff000
	s_addc_u32 s83, s31, 0
	v_lshl_add_u64 v[184:185], s[30:31], 0, v[0:1]
	s_mov_b64 s[12:13], 0
	s_mov_b32 s53, 0x2bbff000
	s_mov_b32 s18, 0x3dd2d3e8
	s_mov_b32 s22, 0xc0135761
	s_movk_i32 s54, 0x80
	s_mov_b32 s55, 0x7050301
	s_mov_b64 s[38:39], 0x4c3fffe0
	s_mov_b64 s[40:41], 0x4c3ffc00
	s_mov_b64 s[42:43], 0x4c3ffbe0
	v_add_u32_e32 v235, v205, v2
	v_add_u32_e32 v236, v205, v3
	v_add_u32_e32 v234, v205, v6
	v_add_u32_e32 v233, v205, v7
	v_add_u32_e32 v169, v205, v10
	v_add_u32_e32 v171, v205, v11
	v_add_u32_e32 v163, v205, v12
	v_add_u32_e32 v167, v205, v13
	v_mov_b64_e32 v[180:181], v[176:177]
	v_mov_b64_e32 v[188:189], v[176:177]
	v_mov_b64_e32 v[192:193], v[176:177]
	v_mov_b64_e32 v[178:179], v[176:177]
	v_mov_b64_e32 v[182:183], v[176:177]
	v_mov_b64_e32 v[186:187], v[176:177]
	v_mov_b64_e32 v[190:191], v[176:177]
	v_mov_b32_e32 v202, v165
	v_mov_b32_e32 v203, v164
	s_waitcnt vmcnt(0)
	s_branch .LBB0_381

; template <bool REV> ...
;     ...
;     for (int tile = 0; tile < 128; ++tile) {
;         const bool second = tile >= 64;
;         if (tile == 64) {
;             asm volatile("s_waitcnt vmcnt(0)" ::: "memory"); __syncthreads();
;             __builtin_amdgcn_fence(__ATOMIC_ACQUIRE, "agent"); asm volatile("s_waitcnt vmcnt(0)" ::: "memory");
; #pragma unroll
;             for (int th = 0; th < 2; ++th)
; #pragma unroll
;                 for (int sx = 0; sx < 2; ++sx) { pv[th][sx] = *(const u32x2*)(pY + th * CSTEP16 + sx * SSTEP); uv[th][sx] = *(const u32x2*)(pU + th * CSTEP16 + sx * SSTEP); }
;         }
.LBB0_381:
	v_lshl_add_u64 v[198:199], v[184:185], 0, s[12:13]
	v_add_u32_e32 v253, s76, v198
	s_cmp_lg_u32 s12, 0xfffe0000
	v_lshl_add_u64 v[200:201], v[198:199], 0, s[16:17]
	s_cbranch_scc1 .LBB0_383
	s_nop 0
	s_waitcnt vmcnt(0)
	s_nop 1
	s_nop 0
	s_nop 0
	s_barrier
	s_nop 0
	s_nop 0
	s_waitcnt vmcnt(0)
	buffer_inv sc1
	s_waitcnt vmcnt(0)
	s_nop 0
	s_nop 1
	s_nop 0
	global_load_dwordx2 v[192:193], v[200:201], off
	global_load_dwordx2 v[190:191], v253, s[78:79]
	global_load_dwordx2 v[180:181], v253, s[80:81] offset:3072
	global_load_dwordx2 v[176:177], v253, s[80:81] offset:3040
	global_load_dwordx2 v[188:189], v253, s[80:81] offset:4064
	global_load_dwordx2 v[186:187], v253, s[82:83] offset:4064
	global_load_dwordx2 v[182:183], v253, s[82:83] offset:3072
	global_load_dwordx2 v[178:179], v253, s[82:83] offset:3040
	s_waitcnt vmcnt(0)

; __device__ __forceinline__ unsigned cvt_pk_bf16(float lo, float hi) { unsigned r; asm volatile("v_cvt_pk_bf16_f32 %0, %1, %2" : "=v"(r) : "v"(lo), "v"(hi)); return r; }
; __device__ __forceinline__ unsigned cvt_pk_bf16_mfma(float lo, float hi) { unsigned r; asm volatile("s_nop 7\n\ts_nop 4\n\tv_cvt_pk_bf16_f32 %0, %1, %2" : "=v"(r) : "v"(lo), "v"(hi)); return r; }
; __device__ __forceinline__ float bf_lo(unsigned w) { return __uint_as_float(w << 16); }
; __device__ __forceinline__ float bf_hi(unsigned w) { return __uint_as_float(w & 0xffff0000u); }
; template <bool REV> ...
;     ...
;                 if (!second) { u32x2 w; w.x = cvt_pk_bf16_mfma(y[0], y[1]); w.y = cvt_pk_bf16(y[2], y[3]); *(u32x2*)yo = w; }
;                 else { const u32x2 p = pv[th][sx], u = uv[th][sx];
;                     const f32x2 v01 = (f32x2){y[0], y[1]} + (f32x2){bf_lo(p.x), bf_hi(p.x)} + dsk01 * (f32x2){bf_lo(u.x), bf_hi(u.x)};
;                     const f32x2 v23 = (f32x2){y[2], y[3]} + (f32x2){bf_lo(p.y), bf_hi(p.y)} + dsk23 * (f32x2){bf_lo(u.y), bf_hi(u.y)};
;                     const f32x2 o01 = gelu2(v01), o23 = gelu2(v23);
;                     u32x2 w; w.x = cvt_pk_bf16(o01.x, o01.y); w.y = cvt_pk_bf16(o23.x, o23.y); *(u32x2*)yo = w;
;                     { const unsigned x8 = pack_i8x4(o01.x, o01.y, o23.x, o23.y, 1.0f / YA8_R);
;                       *(unsigned*)(Y8 + (yo - YA)) = x8; }
;                     pv[th][sx] = *(const u32x2*)(yo + adv); uv[th][sx] = *(const u32x2*)(pU + th * CSTEP16 + sx * SSTEP + adv); }
;             }
;             Ub[th] = *(const bf16x8*)(pB + th * CSTEP16 + adv);
.LBB0_385:
	s_andn2_b64 vcc, exec, s[0:1]
	s_cbranch_vccnz .LBB0_387
	v_lshlrev_b32_e32 v24, 16, v192
	v_and_b32_e32 v25, 0xffff0000, v192
	s_nop 2
	v_pk_add_f32 v[20:21], v[20:21], v[24:25]
	v_lshlrev_b32_e32 v24, 16, v190
	v_and_b32_e32 v25, 0xffff0000, v190
	v_pk_fma_f32 v[20:21], v[64:65], v[24:25], v[20:21]
	v_lshlrev_b32_e32 v24, 16, v193
	v_and_b32_e32 v25, 0xffff0000, v193
	v_pk_add_f32 v[22:23], v[22:23], v[24:25]
	v_lshlrev_b32_e32 v24, 16, v191
	v_and_b32_e32 v25, 0xffff0000, v191
	v_pk_fma_f32 v[22:23], v[66:67], v[24:25], v[22:23]
	v_pk_mul_f32 v[24:25], v[20:21], v[20:21]
	v_mov_b64_e32 v[26:27], s[22:23]
	v_pk_fma_f32 v[24:25], v[24:25], s[18:19], v[26:27] op_sel_hi:[1,0,0] neg_lo:[1,0,0] neg_hi:[1,0,0]
	v_pk_mul_f32 v[28:29], v[22:23], v[22:23]
	v_pk_mul_f32 v[24:25], v[20:21], v[24:25]
	v_pk_fma_f32 v[26:27], v[28:29], s[18:19], v[26:27] op_sel_hi:[1,0,0] neg_lo:[1,0,0] neg_hi:[1,0,0]
	v_exp_f32_e32 v24, v24
	v_exp_f32_e32 v25, v25
	v_pk_mul_f32 v[26:27], v[22:23], v[26:27]
	v_pk_add_f32 v[24:25], v[24:25], 1.0 op_sel_hi:[1,0]
	v_exp_f32_e32 v26, v26
	v_exp_f32_e32 v27, v27
	v_rcp_f32_e32 v24, v24
	v_rcp_f32_e32 v25, v25
	v_pk_add_f32 v[26:27], v[26:27], 1.0 op_sel_hi:[1,0]
	s_nop 0
	v_rcp_f32_e32 v26, v26
	v_rcp_f32_e32 v27, v27
	v_pk_mul_f32 v[20:21], v[20:21], v[24:25]
	v_pk_mul_f32 v[22:23], v[22:23], v[26:27]
	v_cvt_pk_bf16_f32 v24, v20, v21
	v_mul_f32_e32 v14, 0x3d924925, v20
	v_mul_f32_e32 v20, 0x3d924925, v21
	v_cvt_pknorm_i16_f32 v14, v14, v20
	v_mul_f32_e32 v20, 0x3d924925, v22
	v_mul_f32_e32 v21, 0x3d924925, v23
	v_cvt_pknorm_i16_f32 v20, v20, v21
	v_pk_add_i16 v14, v14, s54 op_sel_hi:[1,0] clamp
	v_pk_add_i16 v20, v20, s54 op_sel_hi:[1,0] clamp
	v_mov_b32_e32 v21, s7
	v_perm_b32 v14, v20, v14, s55
	v_subrev_u32_e32 v20, s6, v200
	v_cvt_pk_bf16_f32 v25, v22, v23
	global_store_dwordx2 v[200:201], v[24:25], off
	s_nop 0
	s_nop 0
	v_lshrrev_b32_e32 v20, 1, v20
	s_nop 0
	global_store_dword v20, v14, s[8:9]
	s_nop 0
	s_nop 1
	s_nop 0
	s_nop 0
	s_nop 1
	s_nop 0
	global_load_dwordx2 v[192:193], v253, s[80:81] offset:2048
	global_load_dwordx2 v[190:191], v253, s[82:83] offset:2048

; __device__ __forceinline__ unsigned cvt_pk_bf16(float lo, float hi) { unsigned r; asm volatile("v_cvt_pk_bf16_f32 %0, %1, %2" : "=v"(r) : "v"(lo), "v"(hi)); return r; }
; __device__ __forceinline__ unsigned cvt_pk_bf16_mfma(float lo, float hi) { unsigned r; asm volatile("s_nop 7\n\ts_nop 4\n\tv_cvt_pk_bf16_f32 %0, %1, %2" : "=v"(r) : "v"(lo), "v"(hi)); return r; }
; __device__ __forceinline__ float bf_lo(unsigned w) { return __uint_as_float(w << 16); }
; __device__ __forceinline__ float bf_hi(unsigned w) { return __uint_as_float(w & 0xffff0000u); }
; template <bool REV> ...
;     ...
;                 if (!second) { u32x2 w; w.x = cvt_pk_bf16_mfma(y[0], y[1]); w.y = cvt_pk_bf16(y[2], y[3]); *(u32x2*)yo = w; }
;                 else { const u32x2 p = pv[th][sx], u = uv[th][sx];
;                     const f32x2 v01 = (f32x2){y[0], y[1]} + (f32x2){bf_lo(p.x), bf_hi(p.x)} + dsk01 * (f32x2){bf_lo(u.x), bf_hi(u.x)};
;                     const f32x2 v23 = (f32x2){y[2], y[3]} + (f32x2){bf_lo(p.y), bf_hi(p.y)} + dsk23 * (f32x2){bf_lo(u.y), bf_hi(u.y)};
;                     const f32x2 o01 = gelu2(v01), o23 = gelu2(v23);
;                     u32x2 w; w.x = cvt_pk_bf16(o01.x, o01.y); w.y = cvt_pk_bf16(o23.x, o23.y); *(u32x2*)yo = w;
;                     { const unsigned x8 = pack_i8x4(o01.x, o01.y, o23.x, o23.y, 1.0f / YA8_R);
;                       *(unsigned*)(Y8 + (yo - YA)) = x8; }
;                     pv[th][sx] = *(const u32x2*)(yo + adv); uv[th][sx] = *(const u32x2*)(pU + th * CSTEP16 + sx * SSTEP + adv); }
;             }
;             Ub[th] = *(const bf16x8*)(pB + th * CSTEP16 + adv);
.LBB0_389:
	s_andn2_b64 vcc, exec, s[50:51]
	s_cbranch_vccnz .LBB0_391
	v_lshlrev_b32_e32 v4, 16, v188
	v_and_b32_e32 v5, 0xffff0000, v188
	s_nop 2
	v_pk_add_f32 v[0:1], v[0:1], v[4:5]
	v_lshlrev_b32_e32 v4, 16, v186
	v_and_b32_e32 v5, 0xffff0000, v186
	v_pk_fma_f32 v[0:1], v[64:65], v[4:5], v[0:1]
	v_lshlrev_b32_e32 v4, 16, v189
	v_and_b32_e32 v5, 0xffff0000, v189
	v_pk_add_f32 v[2:3], v[2:3], v[4:5]
	v_lshlrev_b32_e32 v4, 16, v187
	v_and_b32_e32 v5, 0xffff0000, v187
	v_pk_fma_f32 v[2:3], v[66:67], v[4:5], v[2:3]
	v_pk_mul_f32 v[4:5], v[0:1], v[0:1]
	v_mov_b64_e32 v[6:7], s[22:23]
	v_pk_fma_f32 v[4:5], v[4:5], s[18:19], v[6:7] op_sel_hi:[1,0,0] neg_lo:[1,0,0] neg_hi:[1,0,0]
	v_pk_mul_f32 v[10:11], v[2:3], v[2:3]
	v_pk_mul_f32 v[4:5], v[0:1], v[4:5]
	v_pk_fma_f32 v[6:7], v[10:11], s[18:19], v[6:7] op_sel_hi:[1,0,0] neg_lo:[1,0,0] neg_hi:[1,0,0]
	v_exp_f32_e32 v4, v4
	v_exp_f32_e32 v5, v5
	v_pk_mul_f32 v[6:7], v[2:3], v[6:7]
	v_pk_add_f32 v[4:5], v[4:5], 1.0 op_sel_hi:[1,0]
	v_exp_f32_e32 v6, v6
	v_exp_f32_e32 v7, v7
	v_rcp_f32_e32 v4, v4
	v_rcp_f32_e32 v5, v5
	v_pk_add_f32 v[6:7], v[6:7], 1.0 op_sel_hi:[1,0]
	s_nop 0
	v_rcp_f32_e32 v6, v6
	v_rcp_f32_e32 v7, v7
	v_pk_mul_f32 v[0:1], v[0:1], v[4:5]
	v_pk_mul_f32 v[2:3], v[2:3], v[6:7]
	v_cvt_pk_bf16_f32 v4, v0, v1
	v_mul_f32_e32 v0, 0x3d924925, v0
	v_mul_f32_e32 v1, 0x3d924925, v1
	v_cvt_pk_bf16_f32 v5, v2, v3
	v_cvt_pknorm_i16_f32 v0, v0, v1
	v_mul_f32_e32 v1, 0x3d924925, v2
	v_mul_f32_e32 v2, 0x3d924925, v3
	v_cvt_pknorm_i16_f32 v1, v1, v2
	v_pk_add_i16 v0, v0, s54 op_sel_hi:[1,0] clamp
	v_pk_add_i16 v1, v1, s54 op_sel_hi:[1,0] clamp
	global_store_dwordx2 v[8:9], v[4:5], off
	v_perm_b32 v2, v1, v0, s55
	v_mov_b32_e32 v1, s7
	v_subrev_u32_e32 v0, s6, v8
	s_nop 1
	s_nop 0
	v_lshrrev_b32_e32 v0, 1, v0
	s_nop 0
	global_store_dword v0, v2, s[8:9]
	s_nop 0
	s_nop 1
	s_nop 0
	s_nop 0
	s_nop 1
	s_nop 0
	global_load_dwordx2 v[188:189], v253, s[80:81] offset:2016
	global_load_dwordx2 v[186:187], v253, s[82:83] offset:2016

; __device__ __forceinline__ unsigned cvt_pk_bf16(float lo, float hi) { unsigned r; asm volatile("v_cvt_pk_bf16_f32 %0, %1, %2" : "=v"(r) : "v"(lo), "v"(hi)); return r; }
; __device__ __forceinline__ unsigned cvt_pk_bf16_mfma(float lo, float hi) { unsigned r; asm volatile("s_nop 7\n\ts_nop 4\n\tv_cvt_pk_bf16_f32 %0, %1, %2" : "=v"(r) : "v"(lo), "v"(hi)); return r; }
; __device__ __forceinline__ float bf_lo(unsigned w) { return __uint_as_float(w << 16); }
; __device__ __forceinline__ float bf_hi(unsigned w) { return __uint_as_float(w & 0xffff0000u); }
; template <bool REV> ...
;     ...
;                 if (!second) { u32x2 w; w.x = cvt_pk_bf16_mfma(y[0], y[1]); w.y = cvt_pk_bf16(y[2], y[3]); *(u32x2*)yo = w; }
;                 else { const u32x2 p = pv[th][sx], u = uv[th][sx];
;                     const f32x2 v01 = (f32x2){y[0], y[1]} + (f32x2){bf_lo(p.x), bf_hi(p.x)} + dsk01 * (f32x2){bf_lo(u.x), bf_hi(u.x)};
;                     const f32x2 v23 = (f32x2){y[2], y[3]} + (f32x2){bf_lo(p.y), bf_hi(p.y)} + dsk23 * (f32x2){bf_lo(u.y), bf_hi(u.y)};
;                     const f32x2 o01 = gelu2(v01), o23 = gelu2(v23);
;                     u32x2 w; w.x = cvt_pk_bf16(o01.x, o01.y); w.y = cvt_pk_bf16(o23.x, o23.y); *(u32x2*)yo = w;
;                     { const unsigned x8 = pack_i8x4(o01.x, o01.y, o23.x, o23.y, 1.0f / YA8_R);
;                       *(unsigned*)(Y8 + (yo - YA)) = x8; }
;                     pv[th][sx] = *(const u32x2*)(yo + adv); uv[th][sx] = *(const u32x2*)(pU + th * CSTEP16 + sx * SSTEP + adv); }
;             }
;             Ub[th] = *(const bf16x8*)(pB + th * CSTEP16 + adv);
.LBB0_393:
	s_andn2_b64 vcc, exec, s[46:47]
	s_cbranch_vccnz .LBB0_395
	v_lshlrev_b32_e32 v28, 16, v180
	v_and_b32_e32 v29, 0xffff0000, v180
	s_nop 2
	v_pk_add_f32 v[20:21], v[20:21], v[28:29]
	v_lshlrev_b32_e32 v28, 16, v182
	v_and_b32_e32 v29, 0xffff0000, v182
	v_pk_fma_f32 v[20:21], v[64:65], v[28:29], v[20:21]
	v_lshlrev_b32_e32 v28, 16, v181
	v_and_b32_e32 v29, 0xffff0000, v181
	v_pk_add_f32 v[22:23], v[22:23], v[28:29]
	v_lshlrev_b32_e32 v28, 16, v183
	v_and_b32_e32 v29, 0xffff0000, v183
	v_pk_fma_f32 v[22:23], v[66:67], v[28:29], v[22:23]
	v_pk_mul_f32 v[28:29], v[20:21], v[20:21]
	v_mov_b64_e32 v[32:33], s[22:23]
	v_pk_fma_f32 v[28:29], v[28:29], s[18:19], v[32:33] op_sel_hi:[1,0,0] neg_lo:[1,0,0] neg_hi:[1,0,0]
	v_pk_mul_f32 v[34:35], v[22:23], v[22:23]
	v_pk_mul_f32 v[28:29], v[20:21], v[28:29]
	v_pk_fma_f32 v[32:33], v[34:35], s[18:19], v[32:33] op_sel_hi:[1,0,0] neg_lo:[1,0,0] neg_hi:[1,0,0]
	v_exp_f32_e32 v28, v28
	v_exp_f32_e32 v29, v29
	v_pk_mul_f32 v[32:33], v[22:23], v[32:33]
	v_pk_add_f32 v[28:29], v[28:29], 1.0 op_sel_hi:[1,0]
	v_exp_f32_e32 v32, v32
	v_exp_f32_e32 v33, v33
	v_rcp_f32_e32 v28, v28
	v_rcp_f32_e32 v29, v29
	v_pk_add_f32 v[32:33], v[32:33], 1.0 op_sel_hi:[1,0]
	s_nop 0
	v_rcp_f32_e32 v32, v32
	v_rcp_f32_e32 v33, v33
	v_pk_mul_f32 v[20:21], v[20:21], v[28:29]
	v_pk_mul_f32 v[22:23], v[22:23], v[32:33]
	v_cvt_pk_bf16_f32 v28, v20, v21
	v_mul_f32_e32 v14, 0x3d924925, v20
	v_mul_f32_e32 v20, 0x3d924925, v21
	v_cvt_pknorm_i16_f32 v14, v14, v20
	v_mul_f32_e32 v20, 0x3d924925, v22
	v_mul_f32_e32 v21, 0x3d924925, v23
	v_cvt_pknorm_i16_f32 v20, v20, v21
	v_pk_add_i16 v14, v14, s54 op_sel_hi:[1,0] clamp
	v_pk_add_i16 v20, v20, s54 op_sel_hi:[1,0] clamp
	v_mov_b32_e32 v21, s7
	v_perm_b32 v14, v20, v14, s55
	v_subrev_u32_e32 v20, s6, v26
	v_cvt_pk_bf16_f32 v29, v22, v23
	global_store_dwordx2 v[26:27], v[28:29], off
	s_nop 0
	s_nop 0
	v_lshrrev_b32_e32 v20, 1, v20
	s_nop 0
	global_store_dword v20, v14, s[8:9]
	s_nop 0
	s_nop 1
	s_nop 0
	s_nop 0
	s_nop 1
	s_nop 0
	global_load_dwordx2 v[180:181], v253, s[80:81] offset:1024
	global_load_dwordx2 v[182:183], v253, s[82:83] offset:1024

; __device__ __forceinline__ unsigned cvt_pk_bf16(float lo, float hi) { unsigned r; asm volatile("v_cvt_pk_bf16_f32 %0, %1, %2" : "=v"(r) : "v"(lo), "v"(hi)); return r; }
; __device__ __forceinline__ unsigned cvt_pk_bf16_mfma(float lo, float hi) { unsigned r; asm volatile("s_nop 7\n\ts_nop 4\n\tv_cvt_pk_bf16_f32 %0, %1, %2" : "=v"(r) : "v"(lo), "v"(hi)); return r; }
; __device__ __forceinline__ float bf_lo(unsigned w) { return __uint_as_float(w << 16); }
; __device__ __forceinline__ float bf_hi(unsigned w) { return __uint_as_float(w & 0xffff0000u); }
; template <bool REV> ...
;     ...
;                 if (!second) { u32x2 w; w.x = cvt_pk_bf16_mfma(y[0], y[1]); w.y = cvt_pk_bf16(y[2], y[3]); *(u32x2*)yo = w; }
;                 else { const u32x2 p = pv[th][sx], u = uv[th][sx];
;                     const f32x2 v01 = (f32x2){y[0], y[1]} + (f32x2){bf_lo(p.x), bf_hi(p.x)} + dsk01 * (f32x2){bf_lo(u.x), bf_hi(u.x)};
;                     const f32x2 v23 = (f32x2){y[2], y[3]} + (f32x2){bf_lo(p.y), bf_hi(p.y)} + dsk23 * (f32x2){bf_lo(u.y), bf_hi(u.y)};
;                     const f32x2 o01 = gelu2(v01), o23 = gelu2(v23);
;                     u32x2 w; w.x = cvt_pk_bf16(o01.x, o01.y); w.y = cvt_pk_bf16(o23.x, o23.y); *(u32x2*)yo = w;
;                     { const unsigned x8 = pack_i8x4(o01.x, o01.y, o23.x, o23.y, 1.0f / YA8_R);
;                       *(unsigned*)(Y8 + (yo - YA)) = x8; }
;                     pv[th][sx] = *(const u32x2*)(yo + adv); uv[th][sx] = *(const u32x2*)(pU + th * CSTEP16 + sx * SSTEP + adv); }
;             }
;             Ub[th] = *(const bf16x8*)(pB + th * CSTEP16 + adv);
.LBB0_397:
	s_andn2_b64 vcc, exec, s[46:47]
	s_cbranch_vccnz .LBB0_380
	v_lshlrev_b32_e32 v4, 16, v176
	v_and_b32_e32 v5, 0xffff0000, v176
	s_nop 2
	v_pk_add_f32 v[0:1], v[0:1], v[4:5]
	v_lshlrev_b32_e32 v4, 16, v178
	v_and_b32_e32 v5, 0xffff0000, v178
	v_pk_fma_f32 v[0:1], v[64:65], v[4:5], v[0:1]
	v_lshlrev_b32_e32 v4, 16, v177
	v_and_b32_e32 v5, 0xffff0000, v177
	v_pk_add_f32 v[2:3], v[2:3], v[4:5]
	v_lshlrev_b32_e32 v4, 16, v179
	v_and_b32_e32 v5, 0xffff0000, v179
	v_pk_fma_f32 v[2:3], v[66:67], v[4:5], v[2:3]
	v_pk_mul_f32 v[4:5], v[0:1], v[0:1]
	v_mov_b64_e32 v[6:7], s[22:23]
	v_pk_fma_f32 v[4:5], v[4:5], s[18:19], v[6:7] op_sel_hi:[1,0,0] neg_lo:[1,0,0] neg_hi:[1,0,0]
	v_pk_mul_f32 v[10:11], v[2:3], v[2:3]
	v_pk_mul_f32 v[4:5], v[0:1], v[4:5]
	v_pk_fma_f32 v[6:7], v[10:11], s[18:19], v[6:7] op_sel_hi:[1,0,0] neg_lo:[1,0,0] neg_hi:[1,0,0]
	v_exp_f32_e32 v4, v4
	v_exp_f32_e32 v5, v5
	v_pk_mul_f32 v[6:7], v[2:3], v[6:7]
	v_pk_add_f32 v[4:5], v[4:5], 1.0 op_sel_hi:[1,0]
	v_exp_f32_e32 v6, v6
	v_exp_f32_e32 v7, v7
	v_rcp_f32_e32 v4, v4
	v_rcp_f32_e32 v5, v5
	v_pk_add_f32 v[6:7], v[6:7], 1.0 op_sel_hi:[1,0]
	s_nop 0
	v_rcp_f32_e32 v6, v6
	v_rcp_f32_e32 v7, v7
	v_pk_mul_f32 v[0:1], v[0:1], v[4:5]
	v_pk_mul_f32 v[2:3], v[2:3], v[6:7]
	v_cvt_pk_bf16_f32 v4, v0, v1
	v_mul_f32_e32 v0, 0x3d924925, v0
	v_mul_f32_e32 v1, 0x3d924925, v1
	v_cvt_pk_bf16_f32 v5, v2, v3
	v_cvt_pknorm_i16_f32 v0, v0, v1
	v_mul_f32_e32 v1, 0x3d924925, v2
	v_mul_f32_e32 v2, 0x3d924925, v3
	v_cvt_pknorm_i16_f32 v1, v1, v2
	v_pk_add_i16 v0, v0, s54 op_sel_hi:[1,0] clamp
	v_pk_add_i16 v1, v1, s54 op_sel_hi:[1,0] clamp
	global_store_dwordx2 v[8:9], v[4:5], off
	v_perm_b32 v2, v1, v0, s55
	v_mov_b32_e32 v1, s7
	v_subrev_u32_e32 v0, s6, v8
	s_nop 1
	s_nop 0
	v_lshrrev_b32_e32 v0, 1, v0
	s_nop 0
	global_store_dword v0, v2, s[8:9]
	s_nop 0
	s_nop 1
	s_nop 0
	s_nop 0
	s_nop 1
	s_nop 0
	global_load_dwordx2 v[176:177], v253, s[80:81] offset:992
	global_load_dwordx2 v[178:179], v253, s[82:83] offset:992
	s_branch .LBB0_380

; #define LAS __attribute__((address_space(3)))
; template <bool REV> ...
;     constexpr int SG = REV ? -1 : 1;
;     constexpr int TSTEP = SG * 64 * 16, CSTEP16 = SG * 32 * 16, SSTEP = SG * 16;
;     const float nli = -li;
;     const int nl = lane & 31, hl = lane >> 5, tk = lane & 15, kq = lane >> 4;
;     const bf16* pA = U + gbase + SG * (2 * nl + hl) * 16;
;     const bf16* pB = U + gbase + SG * (2 * tk + (kq >> 1)) * 16 + 8 * (kq & 1);
;     const bf16* pU = U + gbase + SG * (2 * tk) * 16 + 4 * kq;
;     bf16* pY = YA + gbase + SG * (2 * tk) * 16 + 4 * kq;
;     bf16x8 A0 = *(const bf16x8*)pA, A1 = *(const bf16x8*)(pA + 8);
;     bf16x8 Ub[2]; Ub[0] = *(const bf16x8*)pB; Ub[1] = *(const bf16x8*)(pB + CSTEP16);
;     u32x2 pv[2][2], uv[2][2];
; #pragma unroll
;     for (int th = 0; th < 2; ++th)
; #pragma unroll
;         for (int sx = 0; sx < 2; ++sx) { pv[th][sx] = (u32x2){0u, 0u}; uv[th][sx] = (u32x2){0u, 0u}; }
;     const f32x2 dsk01 = (f32x2){dsk[0], dsk[1]}, dsk23 = (f32x2){dsk[2], dsk[3]};
;     LAS unsigned* wbase = (LAS unsigned*)(my + ((lane & 3) << 2));
; __device__ __forceinline__ void s5_phase(const Args& a, const Ctx& F) {
;     ...
;     const size_t gbase = ((size_t)(b * NG + g) * SEQ + (d ? SEQ - 1 : 0)) * 16;
;     unsigned char* Y8 = ws + WS_YA8;
;     if (d) s5_latent<true>(U, YA, Y8, gbase, Bf, Cf, Kf, lr, li, hre, him, my, dsk, lane);
;     else s5_latent<false>(U, YA, Y8, gbase, Bf, Cf, Kf, lr, li, hre, him, my, dsk, lane);
.LBB0_401:
	v_lshlrev_b32_e32 v4, 4, v204
	v_lshl_add_u32 v4, v206, 5, v4
	v_ashrrev_i32_e32 v171, 31, v170
	v_ashrrev_i32_e32 v5, 31, v4
	v_lshlrev_b64 v[0:1], 1, v[170:171]
	v_lshlrev_b64 v[4:5], 1, v[4:5]
	v_lshl_add_u64 v[2:3], s[10:11], 0, v[0:1]
	v_lshl_add_u64 v[6:7], s[10:11], 0, v[4:5]
	v_mov_b32_e32 v163, 0
	v_lshl_add_u64 v[6:7], v[6:7], 0, v[162:163]
	global_load_dwordx4 v[152:155], v[2:3], off
	global_load_dwordx4 v[148:151], v[2:3], off offset:16
	global_load_dwordx4 v[144:147], v[6:7], off
	global_load_dwordx4 v[140:143], v[6:7], off offset:1024
	s_add_i32 s0, s19, s33
	s_add_i32 s0, s0, s34
	s_ashr_i32 s1, s0, 31
	s_lshl_b64 s[0:1], s[0:1], 18
	s_or_b32 s0, s0, s23
	s_add_u32 s10, s30, s0
	s_addc_u32 s11, s31, s1
	v_mov_b32_e32 v169, v163
	v_and_b32_e32 v2, 12, v213
	v_lshl_add_u64 v[182:183], s[10:11], 0, v[0:1]
	v_lshl_add_u64 v[0:1], s[0:1], 0, v[168:169]
	v_add_u32_e32 v2, s35, v2
	v_lshl_add_u64 v[0:1], v[0:1], 0, v[4:5]
	v_lshlrev_b32_e32 v162, 6, v206
	v_ashrrev_i32_e32 v167, 31, v166
	v_lshl_add_u32 v232, v212, 2, v2
	v_lshl_add_u32 v231, v214, 2, v2
	v_lshl_add_u32 v230, v215, 2, v2
	v_lshl_add_u32 v229, v216, 2, v2
	v_lshl_add_u32 v216, v217, 2, v2
	v_lshl_add_u32 v215, v218, 2, v2
	v_lshl_add_u32 v214, v219, 2, v2
	v_lshl_add_u32 v213, v220, 2, v2
	v_lshl_add_u32 v212, v221, 2, v2
	v_lshl_add_u32 v204, v222, 2, v2
	v_lshl_add_u32 v203, v223, 2, v2
	v_lshl_add_u32 v202, v224, 2, v2
	v_lshl_add_u32 v197, v225, 2, v2
	v_lshl_add_u32 v196, v226, 2, v2
	v_lshl_add_u32 v195, v227, 2, v2
	v_lshl_add_u32 v194, v228, 2, v2
	v_xor_b32_e32 v2, v208, v207
	v_xor_b32_e32 v3, v211, v208
	v_xor_b32_e32 v6, v210, v208
	v_xor_b32_e32 v7, v209, v208
	v_bitop3_b32 v8, v208, v207, 8 bitop3:0x36
	v_bitop3_b32 v9, v208, v211, 8 bitop3:0x36
	v_bitop3_b32 v10, v208, v210, 8 bitop3:0x36
	v_bitop3_b32 v11, v208, v209, 8 bitop3:0x36
	v_lshl_add_u64 v[184:185], s[30:31], 0, v[0:1]
	v_lshl_add_u64 v[0:1], s[0:1], 0, v[162:163]
	v_lshlrev_b32_e32 v2, 4, v2
	v_lshlrev_b32_e32 v3, 4, v3
	v_lshlrev_b32_e32 v6, 4, v6
	v_lshlrev_b32_e32 v7, 4, v7
	v_lshlrev_b32_e32 v8, 4, v8
	v_lshlrev_b32_e32 v9, 4, v9
	v_lshlrev_b32_e32 v10, 4, v10
	v_lshlrev_b32_e32 v11, 4, v11
	v_lshl_add_u64 v[0:1], v[166:167], 1, v[0:1]
	v_mov_b32_e32 v162, v163
	s_sub_u32 s76, 0x10000000, s30
	s_add_u32 s78, s30, 0x1bc00000
	s_addc_u32 s79, s31, 0
	s_add_u32 s80, s30, 0x3c400000
	s_addc_u32 s81, s31, 0
	v_lshl_add_u64 v[174:175], s[30:31], 0, v[0:1]
	s_mov_b32 s17, 0
	s_mov_b64 s[10:11], 0
	s_mov_b64 s[12:13], 0x4c400000
	s_mov_b32 s19, 0x2bc00000
	s_mov_b32 s16, 0x3dd2d3e8
	s_mov_b32 s18, 0xc0135761
	s_movk_i32 s33, 0x80
	s_mov_b32 s34, 0x7050301
	s_mov_b64 s[22:23], 0x4c400020
	s_mov_b64 s[38:39], 0x4c400400
	s_mov_b64 s[40:41], 0x4c400420
	v_add_u32_e32 v200, v205, v2
	v_add_u32_e32 v201, v205, v3
	v_add_u32_e32 v199, v205, v6
	v_add_u32_e32 v198, v205, v7
	v_add_u32_e32 v192, v205, v8
	v_add_u32_e32 v193, v205, v9
	v_add_u32_e32 v190, v205, v10
	v_add_u32_e32 v191, v205, v11
	v_mov_b64_e32 v[170:171], v[162:163]
	v_mov_b64_e32 v[176:177], v[162:163]
	v_mov_b64_e32 v[180:181], v[162:163]
	v_mov_b64_e32 v[166:167], v[162:163]
	v_mov_b64_e32 v[168:169], v[162:163]
	v_mov_b64_e32 v[172:173], v[162:163]
	v_mov_b64_e32 v[178:179], v[162:163]
	s_waitcnt vmcnt(0)
	s_branch .LBB0_403

; template <bool REV> ...
;     ...
;     for (int tile = 0; tile < 128; ++tile) {
;         const bool second = tile >= 64;
;         if (tile == 64) {
;             asm volatile("s_waitcnt vmcnt(0)" ::: "memory"); __syncthreads();
;             __builtin_amdgcn_fence(__ATOMIC_ACQUIRE, "agent"); asm volatile("s_waitcnt vmcnt(0)" ::: "memory");
; #pragma unroll
;             for (int th = 0; th < 2; ++th)
; #pragma unroll
;                 for (int sx = 0; sx < 2; ++sx) { pv[th][sx] = *(const u32x2*)(pY + th * CSTEP16 + sx * SSTEP); uv[th][sx] = *(const u32x2*)(pU + th * CSTEP16 + sx * SSTEP); }
;         }
.LBB0_403:
	v_lshl_add_u64 v[186:187], v[174:175], 0, s[10:11]
	v_add_u32_e32 v253, s76, v186
	s_cmp_lg_u32 s10, 0x20000
	v_lshl_add_u64 v[188:189], v[186:187], 0, s[12:13]
	s_cbranch_scc1 .LBB0_405
	s_nop 0
	s_waitcnt vmcnt(0)
	s_nop 1
	s_nop 0
	s_barrier
	s_waitcnt vmcnt(0)
	buffer_inv sc1
	s_waitcnt vmcnt(0)
	s_nop 0
	s_nop 1
	s_nop 0
	global_load_dwordx2 v[180:181], v[188:189], off
	global_load_dwordx2 v[178:179], v253, s[78:79]
	global_load_dwordx2 v[172:173], v253, s[78:79] offset:32
	global_load_dwordx2 v[168:169], v253, s[78:79] offset:1024
	global_load_dwordx2 v[176:177], v253, s[80:81] offset:32
	global_load_dwordx2 v[170:171], v253, s[80:81] offset:1024
	global_load_dwordx2 v[162:163], v253, s[80:81] offset:1056
	global_load_dwordx2 v[166:167], v253, s[78:79] offset:1056
	s_waitcnt vmcnt(0)

; __device__ __forceinline__ unsigned cvt_pk_bf16(float lo, float hi) { unsigned r; asm volatile("v_cvt_pk_bf16_f32 %0, %1, %2" : "=v"(r) : "v"(lo), "v"(hi)); return r; }
; __device__ __forceinline__ unsigned cvt_pk_bf16_mfma(float lo, float hi) { unsigned r; asm volatile("s_nop 7\n\ts_nop 4\n\tv_cvt_pk_bf16_f32 %0, %1, %2" : "=v"(r) : "v"(lo), "v"(hi)); return r; }
; __device__ __forceinline__ float bf_lo(unsigned w) { return __uint_as_float(w << 16); }
; __device__ __forceinline__ float bf_hi(unsigned w) { return __uint_as_float(w & 0xffff0000u); }
; template <bool REV> ...
;     ...
;                 if (!second) { u32x2 w; w.x = cvt_pk_bf16_mfma(y[0], y[1]); w.y = cvt_pk_bf16(y[2], y[3]); *(u32x2*)yo = w; }
;                 else { const u32x2 p = pv[th][sx], u = uv[th][sx];
;                     const f32x2 v01 = (f32x2){y[0], y[1]} + (f32x2){bf_lo(p.x), bf_hi(p.x)} + dsk01 * (f32x2){bf_lo(u.x), bf_hi(u.x)};
;                     const f32x2 v23 = (f32x2){y[2], y[3]} + (f32x2){bf_lo(p.y), bf_hi(p.y)} + dsk23 * (f32x2){bf_lo(u.y), bf_hi(u.y)};
;                     const f32x2 o01 = gelu2(v01), o23 = gelu2(v23);
;                     u32x2 w; w.x = cvt_pk_bf16(o01.x, o01.y); w.y = cvt_pk_bf16(o23.x, o23.y); *(u32x2*)yo = w;
;                     { const unsigned x8 = pack_i8x4(o01.x, o01.y, o23.x, o23.y, 1.0f / YA8_R);
;                       *(unsigned*)(Y8 + (yo - YA)) = x8; }
;                     pv[th][sx] = *(const u32x2*)(yo + adv); uv[th][sx] = *(const u32x2*)(pU + th * CSTEP16 + sx * SSTEP + adv); }
;             }
;             Ub[th] = *(const bf16x8*)(pB + th * CSTEP16 + adv);
.LBB0_407:
	s_andn2_b64 vcc, exec, s[0:1]
	s_cbranch_vccnz .LBB0_409
	v_lshlrev_b32_e32 v24, 16, v180
	v_and_b32_e32 v25, 0xffff0000, v180
	s_nop 2
	v_pk_add_f32 v[20:21], v[20:21], v[24:25]
	v_lshlrev_b32_e32 v24, 16, v178
	v_and_b32_e32 v25, 0xffff0000, v178
	v_pk_fma_f32 v[20:21], v[64:65], v[24:25], v[20:21]
	v_lshlrev_b32_e32 v24, 16, v181
	v_and_b32_e32 v25, 0xffff0000, v181
	v_pk_add_f32 v[22:23], v[22:23], v[24:25]
	v_lshlrev_b32_e32 v24, 16, v179
	v_and_b32_e32 v25, 0xffff0000, v179
	v_pk_fma_f32 v[22:23], v[66:67], v[24:25], v[22:23]
	v_pk_mul_f32 v[24:25], v[20:21], v[20:21]
	v_mov_b64_e32 v[26:27], s[18:19]
	v_pk_fma_f32 v[24:25], v[24:25], s[16:17], v[26:27] op_sel_hi:[1,0,0] neg_lo:[1,0,0] neg_hi:[1,0,0]
	v_pk_mul_f32 v[28:29], v[22:23], v[22:23]
	v_pk_mul_f32 v[24:25], v[20:21], v[24:25]
	v_pk_fma_f32 v[26:27], v[28:29], s[16:17], v[26:27] op_sel_hi:[1,0,0] neg_lo:[1,0,0] neg_hi:[1,0,0]
	v_exp_f32_e32 v24, v24
	v_exp_f32_e32 v25, v25
	v_pk_mul_f32 v[26:27], v[22:23], v[26:27]
	v_pk_add_f32 v[24:25], v[24:25], 1.0 op_sel_hi:[1,0]
	v_exp_f32_e32 v26, v26
	v_exp_f32_e32 v27, v27
	v_rcp_f32_e32 v24, v24
	v_rcp_f32_e32 v25, v25
	v_pk_add_f32 v[26:27], v[26:27], 1.0 op_sel_hi:[1,0]
	s_nop 0
	v_rcp_f32_e32 v26, v26
	v_rcp_f32_e32 v27, v27
	v_pk_mul_f32 v[20:21], v[20:21], v[24:25]
	v_pk_mul_f32 v[22:23], v[22:23], v[26:27]
	v_cvt_pk_bf16_f32 v24, v20, v21
	v_mul_f32_e32 v14, 0x3d924925, v20
	v_mul_f32_e32 v20, 0x3d924925, v21
	v_cvt_pknorm_i16_f32 v14, v14, v20
	v_mul_f32_e32 v20, 0x3d924925, v22
	v_mul_f32_e32 v21, 0x3d924925, v23
	v_cvt_pknorm_i16_f32 v20, v20, v21
	v_pk_add_i16 v14, v14, s33 op_sel_hi:[1,0] clamp
	v_pk_add_i16 v20, v20, s33 op_sel_hi:[1,0] clamp
	v_mov_b32_e32 v21, s7
	v_perm_b32 v14, v20, v14, s34
	v_subrev_u32_e32 v20, s6, v188
	v_cvt_pk_bf16_f32 v25, v22, v23
	global_store_dwordx2 v[188:189], v[24:25], off
	s_nop 0
	s_nop 0
	v_lshrrev_b32_e32 v20, 1, v20
	s_nop 0
	global_store_dword v20, v14, s[8:9]
	s_nop 0
	s_nop 1
	s_nop 0
	s_nop 0
	s_nop 1
	s_nop 0
	global_load_dwordx2 v[180:181], v253, s[80:81] offset:2048
	global_load_dwordx2 v[178:179], v253, s[78:79] offset:2048

; __device__ __forceinline__ unsigned cvt_pk_bf16(float lo, float hi) { unsigned r; asm volatile("v_cvt_pk_bf16_f32 %0, %1, %2" : "=v"(r) : "v"(lo), "v"(hi)); return r; }
; __device__ __forceinline__ unsigned cvt_pk_bf16_mfma(float lo, float hi) { unsigned r; asm volatile("s_nop 7\n\ts_nop 4\n\tv_cvt_pk_bf16_f32 %0, %1, %2" : "=v"(r) : "v"(lo), "v"(hi)); return r; }
; __device__ __forceinline__ float bf_lo(unsigned w) { return __uint_as_float(w << 16); }
; __device__ __forceinline__ float bf_hi(unsigned w) { return __uint_as_float(w & 0xffff0000u); }
; template <bool REV> ...
;     ...
;                 if (!second) { u32x2 w; w.x = cvt_pk_bf16_mfma(y[0], y[1]); w.y = cvt_pk_bf16(y[2], y[3]); *(u32x2*)yo = w; }
;                 else { const u32x2 p = pv[th][sx], u = uv[th][sx];
;                     const f32x2 v01 = (f32x2){y[0], y[1]} + (f32x2){bf_lo(p.x), bf_hi(p.x)} + dsk01 * (f32x2){bf_lo(u.x), bf_hi(u.x)};
;                     const f32x2 v23 = (f32x2){y[2], y[3]} + (f32x2){bf_lo(p.y), bf_hi(p.y)} + dsk23 * (f32x2){bf_lo(u.y), bf_hi(u.y)};
;                     const f32x2 o01 = gelu2(v01), o23 = gelu2(v23);
;                     u32x2 w; w.x = cvt_pk_bf16(o01.x, o01.y); w.y = cvt_pk_bf16(o23.x, o23.y); *(u32x2*)yo = w;
;                     { const unsigned x8 = pack_i8x4(o01.x, o01.y, o23.x, o23.y, 1.0f / YA8_R);
;                       *(unsigned*)(Y8 + (yo - YA)) = x8; }
;                     pv[th][sx] = *(const u32x2*)(yo + adv); uv[th][sx] = *(const u32x2*)(pU + th * CSTEP16 + sx * SSTEP + adv); }
;             }
;             Ub[th] = *(const bf16x8*)(pB + th * CSTEP16 + adv);
.LBB0_411:
	s_andn2_b64 vcc, exec, s[46:47]
	s_cbranch_vccnz .LBB0_413
	v_lshlrev_b32_e32 v4, 16, v176
	v_and_b32_e32 v5, 0xffff0000, v176
	s_nop 2
	v_pk_add_f32 v[0:1], v[0:1], v[4:5]
	v_lshlrev_b32_e32 v4, 16, v172
	v_and_b32_e32 v5, 0xffff0000, v172
	v_pk_fma_f32 v[0:1], v[64:65], v[4:5], v[0:1]
	v_lshlrev_b32_e32 v4, 16, v177
	v_and_b32_e32 v5, 0xffff0000, v177
	v_pk_add_f32 v[2:3], v[2:3], v[4:5]
	v_lshlrev_b32_e32 v4, 16, v173
	v_and_b32_e32 v5, 0xffff0000, v173
	v_pk_fma_f32 v[2:3], v[66:67], v[4:5], v[2:3]
	v_pk_mul_f32 v[4:5], v[0:1], v[0:1]
	v_mov_b64_e32 v[6:7], s[18:19]
	v_pk_fma_f32 v[4:5], v[4:5], s[16:17], v[6:7] op_sel_hi:[1,0,0] neg_lo:[1,0,0] neg_hi:[1,0,0]
	v_pk_mul_f32 v[10:11], v[2:3], v[2:3]
	v_pk_mul_f32 v[4:5], v[0:1], v[4:5]
	v_pk_fma_f32 v[6:7], v[10:11], s[16:17], v[6:7] op_sel_hi:[1,0,0] neg_lo:[1,0,0] neg_hi:[1,0,0]
	v_exp_f32_e32 v4, v4
	v_exp_f32_e32 v5, v5
	v_pk_mul_f32 v[6:7], v[2:3], v[6:7]
	v_pk_add_f32 v[4:5], v[4:5], 1.0 op_sel_hi:[1,0]
	v_exp_f32_e32 v6, v6
	v_exp_f32_e32 v7, v7
	v_rcp_f32_e32 v4, v4
	v_rcp_f32_e32 v5, v5
	v_pk_add_f32 v[6:7], v[6:7], 1.0 op_sel_hi:[1,0]
	s_nop 0
	v_rcp_f32_e32 v6, v6
	v_rcp_f32_e32 v7, v7
	v_pk_mul_f32 v[0:1], v[0:1], v[4:5]
	v_pk_mul_f32 v[2:3], v[2:3], v[6:7]
	v_cvt_pk_bf16_f32 v4, v0, v1
	v_mul_f32_e32 v0, 0x3d924925, v0
	v_mul_f32_e32 v1, 0x3d924925, v1
	v_cvt_pk_bf16_f32 v5, v2, v3
	v_cvt_pknorm_i16_f32 v0, v0, v1
	v_mul_f32_e32 v1, 0x3d924925, v2
	v_mul_f32_e32 v2, 0x3d924925, v3
	v_cvt_pknorm_i16_f32 v1, v1, v2
	v_pk_add_i16 v0, v0, s33 op_sel_hi:[1,0] clamp
	v_pk_add_i16 v1, v1, s33 op_sel_hi:[1,0] clamp
	global_store_dwordx2 v[8:9], v[4:5], off
	v_perm_b32 v2, v1, v0, s34
	v_mov_b32_e32 v1, s7
	v_subrev_u32_e32 v0, s6, v8
	s_nop 1
	s_nop 0
	v_lshrrev_b32_e32 v0, 1, v0
	s_nop 0
	global_store_dword v0, v2, s[8:9]
	s_nop 0
	s_nop 1
	s_nop 0
	s_nop 0
	s_nop 1
	s_nop 0
	global_load_dwordx2 v[176:177], v253, s[80:81] offset:2080
	global_load_dwordx2 v[172:173], v253, s[78:79] offset:2080

; __device__ __forceinline__ unsigned cvt_pk_bf16(float lo, float hi) { unsigned r; asm volatile("v_cvt_pk_bf16_f32 %0, %1, %2" : "=v"(r) : "v"(lo), "v"(hi)); return r; }
; __device__ __forceinline__ unsigned cvt_pk_bf16_mfma(float lo, float hi) { unsigned r; asm volatile("s_nop 7\n\ts_nop 4\n\tv_cvt_pk_bf16_f32 %0, %1, %2" : "=v"(r) : "v"(lo), "v"(hi)); return r; }
; __device__ __forceinline__ float bf_lo(unsigned w) { return __uint_as_float(w << 16); }
; __device__ __forceinline__ float bf_hi(unsigned w) { return __uint_as_float(w & 0xffff0000u); }
; template <bool REV> ...
;     ...
;                 if (!second) { u32x2 w; w.x = cvt_pk_bf16_mfma(y[0], y[1]); w.y = cvt_pk_bf16(y[2], y[3]); *(u32x2*)yo = w; }
;                 else { const u32x2 p = pv[th][sx], u = uv[th][sx];
;                     const f32x2 v01 = (f32x2){y[0], y[1]} + (f32x2){bf_lo(p.x), bf_hi(p.x)} + dsk01 * (f32x2){bf_lo(u.x), bf_hi(u.x)};
;                     const f32x2 v23 = (f32x2){y[2], y[3]} + (f32x2){bf_lo(p.y), bf_hi(p.y)} + dsk23 * (f32x2){bf_lo(u.y), bf_hi(u.y)};
;                     const f32x2 o01 = gelu2(v01), o23 = gelu2(v23);
;                     u32x2 w; w.x = cvt_pk_bf16(o01.x, o01.y); w.y = cvt_pk_bf16(o23.x, o23.y); *(u32x2*)yo = w;
;                     { const unsigned x8 = pack_i8x4(o01.x, o01.y, o23.x, o23.y, 1.0f / YA8_R);
;                       *(unsigned*)(Y8 + (yo - YA)) = x8; }
;                     pv[th][sx] = *(const u32x2*)(yo + adv); uv[th][sx] = *(const u32x2*)(pU + th * CSTEP16 + sx * SSTEP + adv); }
;             }
;             Ub[th] = *(const bf16x8*)(pB + th * CSTEP16 + adv);
.LBB0_415:
	s_andn2_b64 vcc, exec, s[42:43]
	s_cbranch_vccnz .LBB0_417
	v_lshlrev_b32_e32 v28, 16, v170
	v_and_b32_e32 v29, 0xffff0000, v170
	s_nop 2
	v_pk_add_f32 v[20:21], v[20:21], v[28:29]
	v_lshlrev_b32_e32 v28, 16, v168
	v_and_b32_e32 v29, 0xffff0000, v168
	v_pk_fma_f32 v[20:21], v[64:65], v[28:29], v[20:21]
	v_lshlrev_b32_e32 v28, 16, v171
	v_and_b32_e32 v29, 0xffff0000, v171
	v_pk_add_f32 v[22:23], v[22:23], v[28:29]
	v_lshlrev_b32_e32 v28, 16, v169
	v_and_b32_e32 v29, 0xffff0000, v169
	v_pk_fma_f32 v[22:23], v[66:67], v[28:29], v[22:23]
	v_pk_mul_f32 v[28:29], v[20:21], v[20:21]
	v_mov_b64_e32 v[32:33], s[18:19]
	v_pk_fma_f32 v[28:29], v[28:29], s[16:17], v[32:33] op_sel_hi:[1,0,0] neg_lo:[1,0,0] neg_hi:[1,0,0]
	v_pk_mul_f32 v[34:35], v[22:23], v[22:23]
	v_pk_mul_f32 v[28:29], v[20:21], v[28:29]
	v_pk_fma_f32 v[32:33], v[34:35], s[16:17], v[32:33] op_sel_hi:[1,0,0] neg_lo:[1,0,0] neg_hi:[1,0,0]
	v_exp_f32_e32 v28, v28
	v_exp_f32_e32 v29, v29
	v_pk_mul_f32 v[32:33], v[22:23], v[32:33]
	v_pk_add_f32 v[28:29], v[28:29], 1.0 op_sel_hi:[1,0]
	v_exp_f32_e32 v32, v32
	v_exp_f32_e32 v33, v33
	v_rcp_f32_e32 v28, v28
	v_rcp_f32_e32 v29, v29
	v_pk_add_f32 v[32:33], v[32:33], 1.0 op_sel_hi:[1,0]
	s_nop 0
	v_rcp_f32_e32 v32, v32
	v_rcp_f32_e32 v33, v33
	v_pk_mul_f32 v[20:21], v[20:21], v[28:29]
	v_pk_mul_f32 v[22:23], v[22:23], v[32:33]
	v_cvt_pk_bf16_f32 v28, v20, v21
	v_mul_f32_e32 v14, 0x3d924925, v20
	v_mul_f32_e32 v20, 0x3d924925, v21
	v_cvt_pknorm_i16_f32 v14, v14, v20
	v_mul_f32_e32 v20, 0x3d924925, v22
	v_mul_f32_e32 v21, 0x3d924925, v23
	v_cvt_pknorm_i16_f32 v20, v20, v21
	v_pk_add_i16 v14, v14, s33 op_sel_hi:[1,0] clamp
	v_pk_add_i16 v20, v20, s33 op_sel_hi:[1,0] clamp
	v_mov_b32_e32 v21, s7
	v_perm_b32 v14, v20, v14, s34
	v_subrev_u32_e32 v20, s6, v26
	v_cvt_pk_bf16_f32 v29, v22, v23
	global_store_dwordx2 v[26:27], v[28:29], off
	s_nop 0
	s_nop 0
	v_lshrrev_b32_e32 v20, 1, v20
	s_nop 0
	global_store_dword v20, v14, s[8:9]
	s_nop 0
	s_nop 1
	s_nop 0
	s_nop 0
	s_nop 1
	s_nop 0
	global_load_dwordx2 v[170:171], v253, s[80:81] offset:3072
	global_load_dwordx2 v[168:169], v253, s[78:79] offset:3072

; __device__ __forceinline__ unsigned cvt_pk_bf16(float lo, float hi) { unsigned r; asm volatile("v_cvt_pk_bf16_f32 %0, %1, %2" : "=v"(r) : "v"(lo), "v"(hi)); return r; }
; __device__ __forceinline__ float bf_lo(unsigned w) { return __uint_as_float(w << 16); }
; __device__ __forceinline__ float bf_hi(unsigned w) { return __uint_as_float(w & 0xffff0000u); }
; __device__ __forceinline__ f32x2 gelu2(f32x2 v) {
;     const f32x2 t = v * v, w = t * (-0.10294324f) + (-2.3022082f), a = v * w;
;     f32x2 e; e.x = __builtin_amdgcn_exp2f(a.x); e.y = __builtin_amdgcn_exp2f(a.y);
;     const f32x2 q = e + 1.0f; f32x2 r; r.x = __builtin_amdgcn_rcpf(q.x); r.y = __builtin_amdgcn_rcpf(q.y);
;     return v * r;
; }
; template <bool REV> ...
;     ...
;                 else { const u32x2 p = pv[th][sx], u = uv[th][sx];
;                     const f32x2 v01 = (f32x2){y[0], y[1]} + (f32x2){bf_lo(p.x), bf_hi(p.x)} + dsk01 * (f32x2){bf_lo(u.x), bf_hi(u.x)};
;                     const f32x2 v23 = (f32x2){y[2], y[3]} + (f32x2){bf_lo(p.y), bf_hi(p.y)} + dsk23 * (f32x2){bf_lo(u.y), bf_hi(u.y)};
;                     const f32x2 o01 = gelu2(v01), o23 = gelu2(v23);
;                     u32x2 w; w.x = cvt_pk_bf16(o01.x, o01.y); w.y = cvt_pk_bf16(o23.x, o23.y); *(u32x2*)yo = w;
;                     { const unsigned x8 = pack_i8x4(o01.x, o01.y, o23.x, o23.y, 1.0f / YA8_R);
;                       *(unsigned*)(Y8 + (yo - YA)) = x8; }
;                     pv[th][sx] = *(const u32x2*)(yo + adv); uv[th][sx] = *(const u32x2*)(pU + th * CSTEP16 + sx * SSTEP + adv); }
.LBB0_419:
	s_andn2_b64 vcc, exec, s[42:43]
	s_cbranch_vccnz .LBB0_402
	v_lshlrev_b32_e32 v4, 16, v162
	v_and_b32_e32 v5, 0xffff0000, v162
	s_nop 2
	v_pk_add_f32 v[0:1], v[0:1], v[4:5]
	v_lshlrev_b32_e32 v4, 16, v166
	v_and_b32_e32 v5, 0xffff0000, v166
	v_pk_fma_f32 v[0:1], v[64:65], v[4:5], v[0:1]
	v_lshlrev_b32_e32 v4, 16, v163
	v_and_b32_e32 v5, 0xffff0000, v163
	v_pk_add_f32 v[2:3], v[2:3], v[4:5]
	v_lshlrev_b32_e32 v4, 16, v167
	v_and_b32_e32 v5, 0xffff0000, v167
	v_pk_fma_f32 v[2:3], v[66:67], v[4:5], v[2:3]
	v_pk_mul_f32 v[4:5], v[0:1], v[0:1]
	v_mov_b64_e32 v[6:7], s[18:19]
	v_pk_fma_f32 v[4:5], v[4:5], s[16:17], v[6:7] op_sel_hi:[1,0,0] neg_lo:[1,0,0] neg_hi:[1,0,0]
	v_pk_mul_f32 v[10:11], v[2:3], v[2:3]
	v_pk_mul_f32 v[4:5], v[0:1], v[4:5]
	v_pk_fma_f32 v[6:7], v[10:11], s[16:17], v[6:7] op_sel_hi:[1,0,0] neg_lo:[1,0,0] neg_hi:[1,0,0]
	v_exp_f32_e32 v4, v4
	v_exp_f32_e32 v5, v5
	v_pk_mul_f32 v[6:7], v[2:3], v[6:7]
	v_pk_add_f32 v[4:5], v[4:5], 1.0 op_sel_hi:[1,0]
	v_exp_f32_e32 v6, v6
	v_exp_f32_e32 v7, v7
	v_rcp_f32_e32 v4, v4
	v_rcp_f32_e32 v5, v5
	v_pk_add_f32 v[6:7], v[6:7], 1.0 op_sel_hi:[1,0]
	s_nop 0
	v_rcp_f32_e32 v6, v6
	v_rcp_f32_e32 v7, v7
	v_pk_mul_f32 v[0:1], v[0:1], v[4:5]
	v_pk_mul_f32 v[2:3], v[2:3], v[6:7]
	v_cvt_pk_bf16_f32 v4, v0, v1
	v_mul_f32_e32 v0, 0x3d924925, v0
	v_mul_f32_e32 v1, 0x3d924925, v1
	v_cvt_pk_bf16_f32 v5, v2, v3
	v_cvt_pknorm_i16_f32 v0, v0, v1
	v_mul_f32_e32 v1, 0x3d924925, v2
	v_mul_f32_e32 v2, 0x3d924925, v3
	v_cvt_pknorm_i16_f32 v1, v1, v2
	v_pk_add_i16 v0, v0, s33 op_sel_hi:[1,0] clamp
	v_pk_add_i16 v1, v1, s33 op_sel_hi:[1,0] clamp
	global_store_dwordx2 v[8:9], v[4:5], off
	v_perm_b32 v2, v1, v0, s34
	v_mov_b32_e32 v1, s7
	v_subrev_u32_e32 v0, s6, v8
	s_nop 1
	s_nop 0
	v_lshrrev_b32_e32 v0, 1, v0
	s_nop 0
	global_store_dword v0, v2, s[8:9]
	s_nop 0
	s_nop 1
	s_nop 0
	s_nop 0
	s_nop 1
	s_nop 0
	global_load_dwordx2 v[162:163], v253, s[80:81] offset:3104
	global_load_dwordx2 v[166:167], v253, s[78:79] offset:3104
	s_branch .LBB0_402
